# first mixer window: third item per workgroup also static (RG-LRU chunk-summary item = own index); the shared counter serves the short attention items and the rest
# speedup vs baseline: 1.0040x; 1.0036x over previous
.LBB0_544:
	s_barrier
	s_and_saveexec_b64 s[0:1], s[14:15]
	s_cbranch_execz .LBB0_548
	v_cmp_le_i32_e32 vcc, 0, v255
	s_cbranch_vccnz .Lar_static
	v_mov_b32_e32 v255, 1
	global_atomic_add v255, v3, v255, s[66:67] sc0
	s_waitcnt vmcnt(0)
	v_cmp_le_u32_e32 vcc, 64, v255
	v_add_u32_e32 v0, 0x400, v255
	v_add_u32_e32 v1, 0x600, v255
	v_cndmask_b32_e32 v0, v0, v1, vcc
	v_mov_b32_e32 v255, -1
	s_branch .Lar_have
.Lar_static:
	v_mov_b32_e32 v0, v255
	v_readlane_b32 s4, v253, 0
	v_cmp_gt_u32_e32 vcc, 0x200, v0
	v_add_u32_e32 v1, 0x200, v0
	s_addk_i32 s4, 0x440
	v_mov_b32_e32 v255, s4
	v_cndmask_b32_e32 v255, v255, v1, vcc
	v_cmp_gt_u32_e32 vcc, 0x400, v0
	v_cndmask_b32_e32 v255, -1, v255, vcc
